# attention: waves 4-7 start each tile body 256 cycles later (de-phase the two waves of a SIMD)
# speedup vs baseline: 1.0045x; 1.0045x over previous
; #define LAS __attribute__((address_space(3)))
; __device__ __forceinline__ void attn_tile(const LAS unsigned char* Kb, const LAS unsigned char* Vb, const LAS f32x4* bp, const bf16x8 (&qr)[4], f32x16 (&o)[2], float& m, float& l, int r32, int hi) {
;     ...
;     for (int j = 0; j < 4; ++j) { const f32x4 t0 = bp[j * 64], t1 = bp[(4 + j) * 64];
;         p0[4 * j] = t0[0]; p0[4 * j + 1] = t0[1]; p0[4 * j + 2] = t0[2]; p0[4 * j + 3] = t0[3]; p1[4 * j] = t1[0]; p1[4 * j + 1] = t1[1]; p1[4 * j + 2] = t1[2]; p1[4 * j + 3] = t1[3]; }
; #pragma unroll
;     for (int d0 = 0; d0 < 4; ++d0) {
;         const bf16x8 a0 = *(const LAS bf16x8*)(Kb + r32 * 144 + d0 * 32 + hi * 16);
;         const bf16x8 a1 = *(const LAS bf16x8*)(Kb + (32 + r32) * 144 + d0 * 32 + hi * 16);
;         p0 = __builtin_amdgcn_mfma_f32_32x32x16_bf16(a0, qr[d0], p0, 0, 0, 0);
;         p1 = __builtin_amdgcn_mfma_f32_32x32x16_bf16(a1, qr[d0], p1, 0, 0, 0);
;     }
;     float mx = fmaxf(p0[0], p1[0]);
; #pragma unroll
;     for (int r = 1; r < 16; ++r) mx = fmaxf(mx, fmaxf(p0[r], p1[r]));
;     mx = fmaxf(mx, __shfl_xor(mx, 32)) * C2;
;     if (__any(mx > m + 8.0f)) {
;         const float mn = fmaxf(m, mx), scl = __builtin_amdgcn_exp2f(m - mn); m = mn; l *= scl;
; #pragma unroll
;         for (int r = 0; r < 16; ++r) { o[0][r] *= scl; o[1][r] *= scl; }
;     }
.LBB0_73:
	s_cmp_lt_i32 s28, s25
	s_cselect_b64 s[30:31], -1, 0
	s_cmp_gt_i32 s28, s23
	s_cselect_b64 s[34:35], -1, 0
	s_or_b64 s[30:31], s[30:31], s[34:35]
	s_and_b64 vcc, exec, s[30:31]
	s_cbranch_vccnz .LBB0_77
	s_add_i32 s29, s22, s26
	s_add_i32 s29, s29, 1
	s_min_i32 s29, s29, 3
	s_cmp_lt_u32 s61, 4
	s_cbranch_scc1 .Latt_nosleep_a
	s_sleep 4
.Latt_nosleep_a:
	v_lshl_add_u32 v158, s29, 14, v103
	ds_read_b128 v[48:51], v158 offset:36864
	ds_read_b128 v[52:55], v158 offset:37888
	ds_read_b128 v[56:59], v158 offset:38912
	ds_read_b128 v[60:63], v158 offset:39936
	ds_read_b128 v[138:141], v116 offset:0
	ds_read_b128 v[142:145], v116 offset:4608
	ds_read_b128 v[32:35], v158 offset:40960
	ds_read_b128 v[36:39], v158 offset:41984
	ds_read_b128 v[40:43], v158 offset:43008
	ds_read_b128 v[44:47], v158 offset:44032
	ds_read_b128 v[146:149], v116 offset:32
	ds_read_b128 v[150:153], v116 offset:4640
	ds_read_b128 v[154:157], v116 offset:64
	ds_read_b128 v[118:121], v116 offset:4672
	ds_read_b128 v[122:125], v116 offset:96
	v_add_u32_e32 v133, v113, v112
	v_xor_b32_e32 v132, 32, v200
	s_waitcnt vmcnt(2) lgkmcnt(10)
	v_mfma_f32_32x32x16_bf16 v[48:63], v[138:141], v[64:67], v[48:63]
	ds_read_b128 v[126:129], v116 offset:4704
	s_waitcnt lgkmcnt(6)
	v_mfma_f32_32x32x16_bf16 v[32:47], v[142:145], v[64:67], v[32:47]
	v_lshlrev_b32_e32 v132, 2, v132
	s_waitcnt lgkmcnt(5)
	v_mfma_f32_32x32x16_bf16 v[48:63], v[146:149], v[68:71], v[48:63]
	s_waitcnt lgkmcnt(4)
	v_mfma_f32_32x32x16_bf16 v[32:47], v[150:153], v[68:71], v[32:47]
	s_waitcnt lgkmcnt(3)
	v_mfma_f32_32x32x16_bf16 v[48:63], v[154:157], v[72:75], v[48:63]
	s_waitcnt lgkmcnt(2)
	v_mfma_f32_32x32x16_bf16 v[32:47], v[118:121], v[72:75], v[32:47]
	s_waitcnt lgkmcnt(1)
	v_mfma_f32_32x32x16_bf16 v[48:63], v[122:125], v[80:83], v[48:63]
	s_waitcnt lgkmcnt(0)
	v_mfma_f32_32x32x16_bf16 v[32:47], v[126:129], v[80:83], v[32:47]
	ds_read_b128 v[138:141], v133 offset:18432
	ds_read_b128 v[142:145], v133 offset:18464
	ds_read_b128 v[146:149], v133 offset:18496
	ds_read_b128 v[150:153], v133 offset:18528
	ds_read_b128 v[154:157], v133 offset:23040
	ds_read_b128 v[118:121], v133 offset:23072
	ds_read_b128 v[122:125], v133 offset:23104
	ds_read_b128 v[126:129], v133 offset:23136
	v_add_f32_e32 v159, 0x41000000, v117
	s_nop 1
	v_max3_f32 v130, v48, v49, v50
	v_max3_f32 v130, v130, v51, v52
	v_max3_f32 v130, v130, v53, v54
	v_max3_f32 v131, v32, v33, v34
	v_max3_f32 v130, v130, v55, v56
	v_max3_f32 v131, v131, v35, v36
	v_max3_f32 v130, v130, v57, v58
	v_max3_f32 v131, v131, v37, v38
	v_max3_f32 v130, v130, v59, v60
	v_max3_f32 v131, v131, v39, v40
	v_max3_f32 v130, v130, v61, v62
	v_max3_f32 v131, v131, v41, v42
	v_max_f32_e32 v130, v130, v63
	v_max3_f32 v131, v131, v43, v44
	v_max3_f32 v131, v131, v45, v46
	v_max_f32_e32 v131, v131, v47
	v_max_f32_e32 v130, v130, v131
	ds_bpermute_b32 v131, v132, v130
	s_waitcnt lgkmcnt(0)
	v_max_f32_e32 v130, v130, v131
	v_mul_f32_e32 v130, 0x3e38aa3b, v130
	v_cmp_gt_f32_e32 vcc, v130, v159
	s_cbranch_vccz .Latt_keep_a
	v_max_f32_e32 v131, v117, v130
	v_sub_f32_e32 v117, v117, v131
	v_exp_f32_e32 v130, v117
	v_mov_b32_e32 v117, v131
	v_mul_f32_e32 v101, v101, v130
	v_pk_mul_f32 v[0:1], v[0:1], v[130:131] op_sel_hi:[1,0]
	v_pk_mul_f32 v[2:3], v[2:3], v[130:131] op_sel_hi:[1,0]
	v_pk_mul_f32 v[4:5], v[4:5], v[130:131] op_sel_hi:[1,0]
	v_pk_mul_f32 v[6:7], v[6:7], v[130:131] op_sel_hi:[1,0]
	v_pk_mul_f32 v[8:9], v[8:9], v[130:131] op_sel_hi:[1,0]
	v_pk_mul_f32 v[10:11], v[10:11], v[130:131] op_sel_hi:[1,0]
	v_pk_mul_f32 v[12:13], v[12:13], v[130:131] op_sel_hi:[1,0]
	v_pk_mul_f32 v[14:15], v[14:15], v[130:131] op_sel_hi:[1,0]
	v_pk_mul_f32 v[16:17], v[16:17], v[130:131] op_sel_hi:[1,0]
	v_pk_mul_f32 v[18:19], v[18:19], v[130:131] op_sel_hi:[1,0]
	v_pk_mul_f32 v[20:21], v[20:21], v[130:131] op_sel_hi:[1,0]
	v_pk_mul_f32 v[22:23], v[22:23], v[130:131] op_sel_hi:[1,0]
	v_pk_mul_f32 v[24:25], v[24:25], v[130:131] op_sel_hi:[1,0]
	v_pk_mul_f32 v[26:27], v[26:27], v[130:131] op_sel_hi:[1,0]
	v_pk_mul_f32 v[28:29], v[28:29], v[130:131] op_sel_hi:[1,0]
	v_pk_mul_f32 v[30:31], v[30:31], v[130:131] op_sel_hi:[1,0]

; #define LAS __attribute__((address_space(3)))
; __device__ __forceinline__ void attn_tile(const LAS unsigned char* Kb, const LAS unsigned char* Vb, const LAS f32x4* bp, const bf16x8 (&qr)[4], f32x16 (&o)[2], float& m, float& l, int r32, int hi) {
;     ...
;     for (int j = 0; j < 4; ++j) { const f32x4 t0 = bp[j * 64], t1 = bp[(4 + j) * 64];
;         p0[4 * j] = t0[0]; p0[4 * j + 1] = t0[1]; p0[4 * j + 2] = t0[2]; p0[4 * j + 3] = t0[3]; p1[4 * j] = t1[0]; p1[4 * j + 1] = t1[1]; p1[4 * j + 2] = t1[2]; p1[4 * j + 3] = t1[3]; }
; #pragma unroll
;     for (int d0 = 0; d0 < 4; ++d0) {
;         const bf16x8 a0 = *(const LAS bf16x8*)(Kb + r32 * 144 + d0 * 32 + hi * 16);
;         const bf16x8 a1 = *(const LAS bf16x8*)(Kb + (32 + r32) * 144 + d0 * 32 + hi * 16);
;         p0 = __builtin_amdgcn_mfma_f32_32x32x16_bf16(a0, qr[d0], p0, 0, 0, 0);
;         p1 = __builtin_amdgcn_mfma_f32_32x32x16_bf16(a1, qr[d0], p1, 0, 0, 0);
;     }
;     float mx = fmaxf(p0[0], p1[0]);
; #pragma unroll
;     for (int r = 1; r < 16; ++r) mx = fmaxf(mx, fmaxf(p0[r], p1[r]));
;     mx = fmaxf(mx, __shfl_xor(mx, 32)) * C2;
;     if (__any(mx > m + 8.0f)) {
;         const float mn = fmaxf(m, mx), scl = __builtin_amdgcn_exp2f(m - mn); m = mn; l *= scl;
; #pragma unroll
;         for (int r = 0; r < 16; ++r) { o[0][r] *= scl; o[1][r] *= scl; }
;     }
.LBB0_79:
	s_add_i32 s29, s28, 1
	s_cmp_lt_i32 s29, s25
	s_cselect_b64 s[30:31], -1, 0
	s_cmp_ge_i32 s28, s23
	s_cselect_b64 s[28:29], -1, 0
	s_or_b64 s[28:29], s[28:29], s[30:31]
	s_and_b64 vcc, exec, s[28:29]
	s_cbranch_vccnz .LBB0_83
	s_add_i32 s28, s22, s26
	s_min_i32 s28, s28, 3
	s_cmp_lt_u32 s61, 4
	s_cbranch_scc1 .Latt_nosleep_b
	s_sleep 4
.Latt_nosleep_b:
	v_lshl_add_u32 v158, s28, 14, v103
	ds_read_b128 v[48:51], v158 offset:36864
	ds_read_b128 v[52:55], v158 offset:37888
	ds_read_b128 v[56:59], v158 offset:38912
	ds_read_b128 v[60:63], v158 offset:39936
	ds_read_b128 v[138:141], v116 offset:9216
	ds_read_b128 v[142:145], v116 offset:13824
	ds_read_b128 v[32:35], v158 offset:40960
	ds_read_b128 v[36:39], v158 offset:41984
	ds_read_b128 v[40:43], v158 offset:43008
	ds_read_b128 v[44:47], v158 offset:44032
	ds_read_b128 v[146:149], v116 offset:9248
	ds_read_b128 v[150:153], v116 offset:13856
	ds_read_b128 v[154:157], v116 offset:9280
	ds_read_b128 v[118:121], v116 offset:13888
	ds_read_b128 v[122:125], v116 offset:9312
	v_add_u32_e32 v133, v113, v112
	v_xor_b32_e32 v132, 32, v200
	s_waitcnt lgkmcnt(10)
	v_mfma_f32_32x32x16_bf16 v[48:63], v[138:141], v[64:67], v[48:63]
	ds_read_b128 v[126:129], v116 offset:13920
	s_waitcnt lgkmcnt(6)
	v_mfma_f32_32x32x16_bf16 v[32:47], v[142:145], v[64:67], v[32:47]
	v_lshlrev_b32_e32 v132, 2, v132
	s_waitcnt lgkmcnt(5)
	v_mfma_f32_32x32x16_bf16 v[48:63], v[146:149], v[68:71], v[48:63]
	s_waitcnt lgkmcnt(4)
	v_mfma_f32_32x32x16_bf16 v[32:47], v[150:153], v[68:71], v[32:47]
	s_waitcnt lgkmcnt(3)
	v_mfma_f32_32x32x16_bf16 v[48:63], v[154:157], v[72:75], v[48:63]
	s_waitcnt lgkmcnt(2)
	v_mfma_f32_32x32x16_bf16 v[32:47], v[118:121], v[72:75], v[32:47]
	s_waitcnt lgkmcnt(1)
	v_mfma_f32_32x32x16_bf16 v[48:63], v[122:125], v[80:83], v[48:63]
	s_waitcnt lgkmcnt(0)
	v_mfma_f32_32x32x16_bf16 v[32:47], v[126:129], v[80:83], v[32:47]
	ds_read_b128 v[138:141], v133 offset:27648
	ds_read_b128 v[142:145], v133 offset:27680
	ds_read_b128 v[146:149], v133 offset:27712
	ds_read_b128 v[150:153], v133 offset:27744
	ds_read_b128 v[154:157], v133 offset:32256
	ds_read_b128 v[118:121], v133 offset:32288
	ds_read_b128 v[122:125], v133 offset:32320
	ds_read_b128 v[126:129], v133 offset:32352
	v_add_f32_e32 v159, 0x41000000, v117
	s_nop 1
	v_max3_f32 v130, v48, v49, v50
	v_max3_f32 v130, v130, v51, v52
	v_max3_f32 v130, v130, v53, v54
	v_max3_f32 v131, v32, v33, v34
	v_max3_f32 v130, v130, v55, v56
	v_max3_f32 v131, v131, v35, v36
	v_max3_f32 v130, v130, v57, v58
	v_max3_f32 v131, v131, v37, v38
	v_max3_f32 v130, v130, v59, v60
	v_max3_f32 v131, v131, v39, v40
	v_max3_f32 v130, v130, v61, v62
	v_max3_f32 v131, v131, v41, v42
	v_max_f32_e32 v130, v130, v63
	v_max3_f32 v131, v131, v43, v44
	v_max3_f32 v131, v131, v45, v46
	v_max_f32_e32 v131, v131, v47
	v_max_f32_e32 v130, v130, v131
	ds_bpermute_b32 v131, v132, v130
	s_waitcnt lgkmcnt(0)
	v_max_f32_e32 v130, v130, v131
	v_mul_f32_e32 v130, 0x3e38aa3b, v130
	v_cmp_gt_f32_e32 vcc, v130, v159
	s_cbranch_vccz .Latt_keep_b
	v_max_f32_e32 v131, v117, v130
	v_sub_f32_e32 v117, v117, v131
	v_exp_f32_e32 v130, v117
	v_mov_b32_e32 v117, v131
	v_mul_f32_e32 v101, v101, v130
	v_pk_mul_f32 v[0:1], v[0:1], v[130:131] op_sel_hi:[1,0]
	v_pk_mul_f32 v[2:3], v[2:3], v[130:131] op_sel_hi:[1,0]
	v_pk_mul_f32 v[4:5], v[4:5], v[130:131] op_sel_hi:[1,0]
	v_pk_mul_f32 v[6:7], v[6:7], v[130:131] op_sel_hi:[1,0]
	v_pk_mul_f32 v[8:9], v[8:9], v[130:131] op_sel_hi:[1,0]
	v_pk_mul_f32 v[10:11], v[10:11], v[130:131] op_sel_hi:[1,0]
	v_pk_mul_f32 v[12:13], v[12:13], v[130:131] op_sel_hi:[1,0]
	v_pk_mul_f32 v[14:15], v[14:15], v[130:131] op_sel_hi:[1,0]
	v_pk_mul_f32 v[16:17], v[16:17], v[130:131] op_sel_hi:[1,0]
	v_pk_mul_f32 v[18:19], v[18:19], v[130:131] op_sel_hi:[1,0]
	v_pk_mul_f32 v[20:21], v[20:21], v[130:131] op_sel_hi:[1,0]
	v_pk_mul_f32 v[22:23], v[22:23], v[130:131] op_sel_hi:[1,0]
	v_pk_mul_f32 v[24:25], v[24:25], v[130:131] op_sel_hi:[1,0]
	v_pk_mul_f32 v[26:27], v[26:27], v[130:131] op_sel_hi:[1,0]
	v_pk_mul_f32 v[28:29], v[28:29], v[130:131] op_sel_hi:[1,0]
	v_pk_mul_f32 v[30:31], v[30:31], v[130:131] op_sel_hi:[1,0]

; #define LAS __attribute__((address_space(3)))
; #define LDS_BARRIER() asm volatile("s_waitcnt lgkmcnt(0)\n\ts_barrier" ::: "memory")
; #define AT_STORE(K_, V_, buf) do { *(LAS bf16x8*)(lds + AT_KOFF + (buf) * 9216 + srow * 144 + sch * 16) = K_; \
;         _Pragma("unroll") for (int j_ = 0; j_ < 8; ++j_) *(LAS short*)(lds + AT_VOFF + (buf) * 9216 + (8 * sch + j_) * 144 + vp * 2) = V_[j_]; } while (0)
; __device__ __forceinline__ void attn_prompt_unit(const Params& P, LAS unsigned char* lds, int li, int b, int h, int g4, const int tid) {
;     ...
;         if (kt + 2 <= kt_hi) AT_STORE(kA, vA, 0);
;         LDS_BARRIER();
;     }
; __device__ __forceinline__ void attn_sample_unit(const Params& P, LAS unsigned char* lds, int li, int b, int h, const int tid) {
;     const int lane = tid & 63, wid = tid >> 6;
;     const bf16_t* QKV = (const bf16_t*)(P.ws + WS_R1); bf16_t* MIX = (bf16_t*)(P.ws + WS_MIX);
;     LAS float* qs = (LAS float*)lds;
;     LAS float* sc = qs + 1024;
;     LAS float* tab = sc + 16 * 528;
;     const size_t rb = (size_t)TP + b * SSEQ;
;     for (int i = tid; i < 1024; i += 512) qs[i] = bf2f(QKV[(rb + (i >> 6)) * NQKV + h * 64 + (i & 63)]);
.LBB0_85:
	s_waitcnt lgkmcnt(0)
	s_barrier
	s_andn2_b64 vcc, exec, s[0:1]
	s_mov_b64 s[0:1], 0xc0000
	s_add_i32 s26, s26, -2
	v_lshl_add_u64 v[106:107], v[106:107], 0, s[0:1]
	s_cbranch_vccz .LBB0_68
	s_mov_b32 s28, s27
	s_branch .LBB0_71
	s_nop 0
	s_nop 0
	s_nop 0
	s_nop 0
	s_nop 0
	s_nop 0
	s_nop 0
	s_nop 0
	s_nop 0
	s_nop 0
.LBB0_87:
	v_readlane_b32 s22, v245, 51
	s_cmpk_lt_i32 s94, 0x80
	v_readlane_b32 s23, v245, 52
	s_cbranch_scc0 .LBB0_122
	s_and_b32 s2, s94, -16
	s_and_b32 s4, s94, 15
	s_ashr_i32 s0, s2, 31
	s_add_u32 s18, s2, 0x8000
	s_addc_u32 s19, s0, 0
	s_movk_i32 s0, 0x400
	v_cmp_gt_i32_e32 vcc, s0, v166
	s_and_saveexec_b64 s[0:1], vcc
	s_movk_i32 s14, 0x1ff
	s_cbranch_execz .LBB0_100
	s_lshl_b32 s12, s4, 7
	v_max_i32_e32 v2, 0x200, v166
	s_add_u32 s12, s64, s12
	v_sub_u32_e32 v2, v2, v166
	s_addc_u32 s13, s65, 0
	v_lshlrev_b32_e32 v160, 1, v164
	v_add_u32_e32 v3, 0x1ff, v2
	v_lshl_add_u64 v[0:1], s[12:13], 0, v[160:161]
	v_cmp_lt_u32_e32 vcc, s14, v3
	s_mov_b64 s[34:35], -1
	v_mov_b32_e32 v2, v166
	s_and_saveexec_b64 s[28:29], vcc
	s_cbranch_execz .LBB0_97
	v_lshrrev_b32_e32 v4, 9, v3
	v_add_u32_e32 v167, 0x200, v166
	v_add_u32_e32 v5, -1, v4
	v_cmp_lt_u32_e32 vcc, 1, v5
	v_mov_b32_e32 v6, 0
	v_mov_b64_e32 v[2:3], v[166:167]
	s_and_saveexec_b64 s[34:35], vcc
	s_cbranch_execz .LBB0_94
	v_lshrrev_b32_e32 v2, 1, v5
	v_add_u32_e32 v2, 1, v2
	v_and_b32_e32 v6, -2, v2
	v_lshl_add_u32 v7, v166, 2, 0
	s_mov_b32 s12, 0
	s_mov_b64 s[38:39], 0
	v_mov_b64_e32 v[2:3], v[166:167]
